# prompt chunk items: next item's z rows touched (L2 prefetch, dword per 16-byte piece) at the start of the output stage; stage-5 LDS read pipelining dropped
# baseline (speedup 1.0000x reference)
; DI unsigned pk2(float a, float b) { f32x2 v = {a, b}; bfv2 r = __builtin_convertvector(v, bfv2); return __builtin_bit_cast(unsigned, r); }
; DI void chunk_item(const Params& p, int l, int item, char* lds) {
;     ...
;   {
;     const f32x4 z4 = (f32x4){0.f, 0.f, 0.f, 0.f};
;     bf16_t* gPT = p.cPT + (size_t)item * 4096;
;     const float wl_c = s_wl[wave * 16 + l15];
; #pragma unroll
;     for (int k1t = 0; k1t < 4; ++k1t) {
;       f32x4 d = mm16(s_XT + k1t * 16 * XLD, XLD, s_BmT + wave * 16 * XLD, XLD, 1, z4, l15, quad);
;       const int k2 = wave * 16 + l15, k1 = k1t * 16 + quad * 4;
;       float o[4];
; #pragma unroll
;       for (int e = 0; e < 4; ++e) o[e] = ((k1 + e == k2 ? 1.f : 0.f) - d[e]) * wl_c;
;       u32x2 ov; ov[0] = pk2(o[0], o[1]); ov[1] = pk2(o[2], o[3]);
;       *(u32x2*)(gPT + k2 * 64 + k1) = ov;
;     }
;     bf16_t* gG = p.cG + (size_t)item * 4096;
; #pragma unroll
;     for (int k2t = 0; k2t < 4; ++k2t) {
;       const f32x4 d1 = mm16(s_KpT + k2t * 16 * XLD, XLD, s_VmT + wave * 16 * XLD, XLD, 1, z4, l15, quad);
;       const f32x4 d2 = mm16(s_BmT + k2t * 16 * XLD, XLD, s_XT + (64 + wave * 16) * XLD, XLD, 1, z4, l15, quad);
;       const int k2 = k2t * 16 + quad * 4, v = wave * 16 + l15;
;       const f32x4 wv = *(const f32x4*)(s_wl + k2);
;       u32x2 ov; ov[0] = pk2((d1[0] - d2[0]) * wv[0], (d1[1] - d2[1]) * wv[1]); ov[1] = pk2((d1[2] - d2[2]) * wv[2], (d1[3] - d2[3]) * wv[3]);
.LBB0_257:
	s_or_b64 exec, exec, s[0:1]
	s_lshl_b64 s[26:27], s[24:25], 1
	s_add_u32 s0, s56, s26
	s_addc_u32 s1, s57, s27
	s_lshl_b32 s20, s44, 4
	v_or_b32_e32 v20, s20, v112
	v_lshlrev_b32_e32 v2, 6, v20
	v_lshlrev_b32_e32 v0, 2, v20
	s_mulk_i32 s44, 0x500
	v_ashrrev_i32_e32 v3, 31, v2
	s_waitcnt lgkmcnt(0)
	s_barrier
	s_add_i32 s68, s22, 0x200
	s_cmp_lt_i32 s68, 0x1000
	s_cbranch_scc0 .Lcpf_skip
	s_lshl_b32 s69, s68, 5
	s_and_b32 s69, s69, 0xfe0
	s_lshl_b32 s70, s68, 2
	s_and_b32 s70, s70, 0xfffff000
	s_lshr_b32 s71, s68, 1
	s_and_b32 s71, s71, 0x1c0
	v_ashrrev_i32_e32 v40, 3, v212
	v_lshlrev_b32_e32 v41, 3, v212
	v_and_b32_e32 v41, 56, v41
	v_add_u32_e32 v40, s69, v40
	v_add_u32_e32 v40, s70, v40
	v_mov_b64_e32 v[42:43], s[10:11]
	v_mad_i64_i32 v[42:43], s[30:31], v40, s94, v[42:43]
	v_or_b32_e32 v44, s71, v41
	v_lshlrev_b32_e32 v44, 1, v44
	v_mov_b32_e32 v45, 0
	v_lshl_add_u64 v[44:45], v[42:43], 0, v[44:45]
	global_load_dword v229, v[44:45], off
	global_load_dword v229, v[44:45], off offset:1024
	global_load_dword v229, v[44:45], off offset:2048
	v_lshlrev_b32_e32 v46, 1, v41
	v_mov_b32_e32 v47, 0
	v_lshl_add_u64 v[46:47], v[42:43], 0, v[46:47]
	global_load_dword v229, v[46:47], off offset:3072
	global_load_dword v229, v[46:47], off offset:3200
.Lcpf_skip:
	ds_read_b32 v10, v0 offset:58880
	v_add3_u32 v12, s44, v125, v117
	v_lshlrev_b64 v[14:15], 1, v[2:3]
	ds_read_b128 v[2:5], v115 offset:48640
	ds_read_b128 v[6:9], v12 offset:20992
	s_waitcnt lgkmcnt(0)
	v_mfma_f32_16x16x32_bf16 v[2:5], v[2:5], v[6:9], 0
	v_lshl_add_u64 v[16:17], s[0:1], 0, v[14:15]
	v_cmp_eq_u32_e32 vcc, v85, v20
	v_cmp_eq_u32_e64 s[0:1], v118, v20
	v_or_b32_e32 v11, 48, v85
	v_cndmask_b32_e64 v18, 0, 1.0, vcc
	v_cndmask_b32_e64 v19, 0, 1.0, s[0:1]
	v_cmp_eq_u32_e32 vcc, v119, v20
	v_cmp_eq_u32_e64 s[0:1], v120, v20
	v_pk_add_f32 v[2:3], v[18:19], v[2:3] neg_lo:[0,1] neg_hi:[0,1]
	v_cndmask_b32_e64 v18, 0, 1.0, vcc
	v_cndmask_b32_e64 v19, 0, 1.0, s[0:1]
	v_pk_add_f32 v[4:5], v[18:19], v[4:5] neg_lo:[0,1] neg_hi:[0,1]
	v_pk_mul_f32 v[2:3], v[10:11], v[2:3] op_sel_hi:[0,1]
	v_pk_mul_f32 v[4:5], v[10:11], v[4:5] op_sel_hi:[0,1]
	v_lshlrev_b32_e32 v0, 1, v85
	v_cvt_pk_bf16_f32 v2, v2, v3
	v_cvt_pk_bf16_f32 v3, v4, v5
	v_lshl_add_u64 v[16:17], v[16:17], 0, v[0:1]
	global_store_dwordx2 v[16:17], v[2:3], off
	ds_read_b128 v[2:5], v115 offset:49920
	s_waitcnt lgkmcnt(0)
	v_mfma_f32_16x16x32_bf16 v[2:5], v[2:5], v[6:9], 0
	v_cmp_eq_u32_e32 vcc, v121, v20
	v_cmp_eq_u32_e64 s[0:1], v122, v20
	v_or_b32_e32 v13, 32, v85
	v_cndmask_b32_e64 v18, 0, 1.0, vcc
	v_cndmask_b32_e64 v19, 0, 1.0, s[0:1]
	v_cmp_eq_u32_e32 vcc, v123, v20
	v_cmp_eq_u32_e64 s[0:1], v124, v20
	s_nop 0
	v_pk_add_f32 v[2:3], v[18:19], v[2:3] neg_lo:[0,1] neg_hi:[0,1]
	v_cndmask_b32_e64 v18, 0, 1.0, vcc
	v_cndmask_b32_e64 v19, 0, 1.0, s[0:1]
	v_pk_add_f32 v[4:5], v[18:19], v[4:5] neg_lo:[0,1] neg_hi:[0,1]
	v_pk_mul_f32 v[2:3], v[10:11], v[2:3] op_sel_hi:[0,1]
	v_pk_mul_f32 v[4:5], v[10:11], v[4:5] op_sel_hi:[0,1]
	v_cvt_pk_bf16_f32 v2, v2, v3
	v_cvt_pk_bf16_f32 v3, v4, v5
	global_store_dwordx2 v[16:17], v[2:3], off offset:32
	ds_read_b128 v[2:5], v115 offset:51200
	s_waitcnt lgkmcnt(0)
	v_mfma_f32_16x16x32_bf16 v[2:5], v[2:5], v[6:9], 0
	v_or_b32_e32 v18, 33, v85
	v_cmp_eq_u32_e32 vcc, v13, v20
	v_cmp_eq_u32_e64 s[0:1], v18, v20
	v_or_b32_e32 v13, 35, v85
	v_cndmask_b32_e64 v18, 0, 1.0, vcc
	v_cndmask_b32_e64 v19, 0, 1.0, s[0:1]
	s_nop 1
	v_pk_add_f32 v[2:3], v[18:19], v[2:3] neg_lo:[0,1] neg_hi:[0,1]
	v_or_b32_e32 v18, 34, v85
	v_cmp_eq_u32_e32 vcc, v18, v20
	v_cmp_eq_u32_e64 s[0:1], v13, v20
	v_pk_mul_f32 v[2:3], v[10:11], v[2:3] op_sel_hi:[0,1]
	v_cndmask_b32_e64 v18, 0, 1.0, vcc
	v_cndmask_b32_e64 v19, 0, 1.0, s[0:1]
	v_pk_add_f32 v[4:5], v[18:19], v[4:5] neg_lo:[0,1] neg_hi:[0,1]
	v_cvt_pk_bf16_f32 v2, v2, v3
	v_pk_mul_f32 v[4:5], v[10:11], v[4:5] op_sel_hi:[0,1]
	v_cvt_pk_bf16_f32 v3, v4, v5
	global_store_dwordx2 v[16:17], v[2:3], off offset:64
	ds_read_b128 v[2:5], v115 offset:52480
	s_waitcnt lgkmcnt(0)
	v_mfma_f32_16x16x32_bf16 v[2:5], v[2:5], v[6:9], 0
	v_or_b32_e32 v6, 49, v85
	v_cmp_eq_u32_e32 vcc, v11, v20
	v_cmp_eq_u32_e64 s[0:1], v6, v20
	v_readlane_b32 s68, v254, 52
	v_cndmask_b32_e64 v6, 0, 1.0, vcc
	v_cndmask_b32_e64 v7, 0, 1.0, s[0:1]
	s_nop 1
	v_pk_add_f32 v[2:3], v[6:7], v[2:3] neg_lo:[0,1] neg_hi:[0,1]
	v_or_b32_e32 v6, 51, v85
	v_or_b32_e32 v7, 50, v85
	v_cmp_eq_u32_e32 vcc, v7, v20
	v_cmp_eq_u32_e64 s[0:1], v6, v20
	v_pk_mul_f32 v[2:3], v[10:11], v[2:3] op_sel_hi:[0,1]
	v_cndmask_b32_e64 v6, 0, 1.0, vcc
	v_cndmask_b32_e64 v7, 0, 1.0, s[0:1]
	v_pk_add_f32 v[4:5], v[6:7], v[4:5] neg_lo:[0,1] neg_hi:[0,1]
	v_cvt_pk_bf16_f32 v2, v2, v3
	v_pk_mul_f32 v[4:5], v[10:11], v[4:5] op_sel_hi:[0,1]
	v_cvt_pk_bf16_f32 v3, v4, v5
	global_store_dwordx2 v[16:17], v[2:3], off offset:96
	ds_read_b128 v[6:9], v115 offset:26112
	ds_read_b128 v[2:5], v12 offset:31232
	s_add_u32 s0, s58, s26
	s_addc_u32 s1, s59, s27
	v_lshl_add_u64 v[10:11], s[0:1], 0, v[14:15]
	s_waitcnt lgkmcnt(0)
	v_mfma_f32_16x16x32_bf16 v[14:17], v[6:9], v[2:5], 0
	ds_read_b128 v[18:21], v115 offset:20992
	ds_read_b128 v[6:9], v12 offset:53760
	ds_read_b128 v[22:25], v89 offset:58880
	v_lshl_add_u64 v[10:11], v[10:11], 0, v[0:1]
	s_waitcnt lgkmcnt(1)
; DI unsigned pk2(float a, float b) { f32x2 v = {a, b}; bfv2 r = __builtin_convertvector(v, bfv2); return __builtin_bit_cast(unsigned, r); }
; DI float bf_lo(unsigned u) { return __uint_as_float(u << 16); }
; DI float bf_hi(unsigned u) { return __uint_as_float(u & 0xffff0000u); }
; DI void chunk_item(const Params& p, int l, int item, char* lds) {
;     ...
;     bf16_t* gG = p.cG + (size_t)item * 4096;
; #pragma unroll
;     for (int k2t = 0; k2t < 4; ++k2t) {
;       const f32x4 d1 = mm16(s_KpT + k2t * 16 * XLD, XLD, s_VmT + wave * 16 * XLD, XLD, 1, z4, l15, quad);
;       const f32x4 d2 = mm16(s_BmT + k2t * 16 * XLD, XLD, s_XT + (64 + wave * 16) * XLD, XLD, 1, z4, l15, quad);
;       const int k2 = k2t * 16 + quad * 4, v = wave * 16 + l15;
;       const f32x4 wv = *(const f32x4*)(s_wl + k2);
;       u32x2 ov; ov[0] = pk2((d1[0] - d2[0]) * wv[0], (d1[1] - d2[1]) * wv[1]); ov[1] = pk2((d1[2] - d2[2]) * wv[2], (d1[3] - d2[3]) * wv[3]);
;       *(u32x2*)(gG + v * 64 + k2) = ov;
;     }
;     bf16_t* gRT = p.cRT + (size_t)item * 2048;
;     bf16_t* gOI = p.cOI + (size_t)item * 2048;
; #pragma unroll
;     for (int ti = 0; ti < 2; ++ti) {
;       const f32x4 d = mm16(s_XT + wave * 16 * XLD, XLD, s_Mrb + ti * 16 * XLD, XLD, 1, z4, l15, quad);
;       const int t = ti * 16 + l15, k = wave * 16 + quad * 4;
;       const u32x2 rv = *(const u32x2*)(s_R + t * 72 + k);
;       u32x2 ov; ov[0] = pk2(bf_lo(rv[0]) - d[0], bf_hi(rv[0]) - d[1]); ov[1] = pk2(bf_lo(rv[1]) - d[2], bf_hi(rv[1]) - d[3]);
;       *(u32x2*)(gRT + t * 64 + k) = ov;
;       const f32x4 e1 = mm16(s_VmT + wave * 16 * XLD, XLD, s_Mrk + ti * 16 * XLD, XLD, 1, z4, l15, quad);
;       const f32x4 e2 = mm16(s_XT + (64 + wave * 16) * XLD, XLD, s_Mrb + ti * 16 * XLD, XLD, 1, z4, l15, quad);
;       u32x2 oo; oo[0] = pk2(e1[0] - e2[0], e1[1] - e2[1]); oo[1] = pk2(e1[2] - e2[2], e1[3] - e2[3]);
;       *(u32x2*)(gOI + t * 64 + k) = oo;
;     }
;   }
;   __syncthreads();
	v_mfma_f32_16x16x32_bf16 v[18:21], v[18:21], v[6:9], 0
	s_add_u32 s0, s60, s24
	s_addc_u32 s1, s61, s25
	v_lshlrev_b32_e32 v0, 1, v113
	s_nop 4
	v_sub_f32_e32 v15, v15, v19
	v_sub_f32_e32 v14, v14, v18
	v_sub_f32_e32 v17, v17, v21
	v_sub_f32_e32 v16, v16, v20
	ds_read_b128 v[18:21], v115 offset:22272
	s_waitcnt lgkmcnt(1)
	v_pk_mul_f32 v[16:17], v[16:17], v[24:25]
	v_pk_mul_f32 v[14:15], v[14:15], v[22:23]
	s_waitcnt lgkmcnt(0)
	v_mfma_f32_16x16x32_bf16 v[18:21], v[18:21], v[6:9], 0
	v_cvt_pk_bf16_f32 v14, v14, v15
	v_cvt_pk_bf16_f32 v15, v16, v17
	global_store_dwordx2 v[10:11], v[14:15], off
	ds_read_b128 v[14:17], v115 offset:27392
	s_waitcnt lgkmcnt(0)
	v_mfma_f32_16x16x32_bf16 v[14:17], v[14:17], v[2:5], 0
	ds_read_b128 v[22:25], v89 offset:58944
	s_add_u32 s24, s62, s24
	s_addc_u32 s25, s63, s25
	s_nop 4
	v_sub_f32_e32 v15, v15, v19
	v_sub_f32_e32 v14, v14, v18
	v_sub_f32_e32 v17, v17, v21
	v_sub_f32_e32 v16, v16, v20
	ds_read_b128 v[18:21], v115 offset:23552
	s_waitcnt lgkmcnt(1)
	v_pk_mul_f32 v[16:17], v[16:17], v[24:25]
	v_pk_mul_f32 v[14:15], v[14:15], v[22:23]
	s_waitcnt lgkmcnt(0)
	v_mfma_f32_16x16x32_bf16 v[18:21], v[18:21], v[6:9], 0
	v_cvt_pk_bf16_f32 v14, v14, v15
	v_cvt_pk_bf16_f32 v15, v16, v17
	global_store_dwordx2 v[10:11], v[14:15], off offset:32
	ds_read_b128 v[14:17], v115 offset:28672
	s_waitcnt lgkmcnt(0)
	v_mfma_f32_16x16x32_bf16 v[14:17], v[14:17], v[2:5], 0
	ds_read_b128 v[22:25], v89 offset:59008
	v_readlane_b32 s74, v254, 58
	s_add_i32 s22, s22, s74
	s_nop 4
	v_sub_f32_e32 v15, v15, v19
	v_sub_f32_e32 v14, v14, v18
	v_sub_f32_e32 v17, v17, v21
	v_sub_f32_e32 v16, v16, v20
	ds_read_b128 v[18:21], v115 offset:24832
	s_waitcnt lgkmcnt(1)
	v_pk_mul_f32 v[16:17], v[16:17], v[24:25]
	v_pk_mul_f32 v[14:15], v[14:15], v[22:23]
	s_waitcnt lgkmcnt(0)
	v_mfma_f32_16x16x32_bf16 v[18:21], v[18:21], v[6:9], 0
	v_cvt_pk_bf16_f32 v14, v14, v15
	v_cvt_pk_bf16_f32 v15, v16, v17
	global_store_dwordx2 v[10:11], v[14:15], off offset:64
	ds_read_b128 v[14:17], v115 offset:29952
	ds_read_b128 v[22:25], v89 offset:59072
	s_waitcnt lgkmcnt(1)
	v_mfma_f32_16x16x32_bf16 v[14:17], v[14:17], v[2:5], 0
	s_cmpk_gt_i32 s22, 0xfff
	v_readlane_b32 s69, v254, 53
	v_readlane_b32 s70, v254, 54
	s_nop 4
	v_sub_f32_e32 v15, v15, v19
	v_sub_f32_e32 v14, v14, v18
	v_sub_f32_e32 v17, v17, v21
	v_sub_f32_e32 v16, v16, v20
	s_waitcnt lgkmcnt(0)
	v_pk_mul_f32 v[16:17], v[16:17], v[24:25]
	v_pk_mul_f32 v[14:15], v[14:15], v[22:23]
	v_readlane_b32 s71, v254, 55
	v_cvt_pk_bf16_f32 v14, v14, v15
	v_cvt_pk_bf16_f32 v15, v16, v17
	global_store_dwordx2 v[10:11], v[14:15], off offset:96
	ds_read_b128 v[18:21], v12 offset:48640
	ds_read_b128 v[22:25], v115 offset:41472
	v_or_b32_e32 v10, s20, v85
	v_ashrrev_i32_e32 v11, 31, v10
	v_lshl_add_u32 v30, v10, 1, v114
	v_lshlrev_b64 v[14:15], 1, v[10:11]
	ds_read_b64 v[10:11], v30 offset:16384
	s_waitcnt lgkmcnt(1)
	v_mfma_f32_16x16x32_bf16 v[26:29], v[18:21], v[22:25], 0
	v_lshl_add_u64 v[16:17], s[0:1], 0, v[14:15]
	v_lshl_add_u64 v[14:15], s[24:25], 0, v[14:15]
	v_readlane_b32 s72, v254, 56
	s_waitcnt lgkmcnt(0)
	v_lshlrev_b32_e32 v12, 16, v10
	v_and_b32_e32 v13, 0xffff0000, v10
	s_nop 1
	v_pk_add_f32 v[12:13], v[12:13], v[26:27] neg_lo:[0,1] neg_hi:[0,1]
	v_mfma_f32_16x16x32_bf16 v[22:25], v[6:9], v[22:25], 0
	v_cvt_pk_bf16_f32 v10, v12, v13
	v_lshlrev_b32_e32 v12, 16, v11
	v_and_b32_e32 v13, 0xffff0000, v11
	v_pk_add_f32 v[12:13], v[12:13], v[28:29] neg_lo:[0,1] neg_hi:[0,1]
	v_readlane_b32 s73, v254, 57
	v_cvt_pk_bf16_f32 v11, v12, v13
	v_lshl_add_u64 v[12:13], v[16:17], 0, v[0:1]
	global_store_dwordx2 v[12:13], v[10:11], off
	ds_read_b128 v[10:13], v115 offset:38912
	s_waitcnt lgkmcnt(0)
	v_mfma_f32_16x16x32_bf16 v[10:13], v[2:5], v[10:13], 0
	v_readlane_b32 s75, v254, 59
	s_nop 6
	v_sub_f32_e32 v13, v13, v25
	v_sub_f32_e32 v12, v12, v24
	v_sub_f32_e32 v11, v11, v23
	v_sub_f32_e32 v10, v10, v22
	v_cvt_pk_bf16_f32 v10, v10, v11
	v_cvt_pk_bf16_f32 v11, v12, v13
	v_lshl_add_u64 v[12:13], v[14:15], 0, v[0:1]
	global_store_dwordx2 v[12:13], v[10:11], off
	ds_read_b128 v[10:13], v115 offset:42752
	ds_read_b64 v[22:23], v30 offset:18688
	s_waitcnt lgkmcnt(1)
	v_mfma_f32_16x16x32_bf16 v[18:21], v[18:21], v[10:13], 0
	s_waitcnt lgkmcnt(0)
	v_lshlrev_b32_e32 v24, 16, v22
	v_and_b32_e32 v25, 0xffff0000, v22
	v_lshlrev_b32_e32 v22, 16, v23
	v_and_b32_e32 v23, 0xffff0000, v23
	s_nop 2
	v_pk_add_f32 v[18:19], v[24:25], v[18:19] neg_lo:[0,1] neg_hi:[0,1]
	v_pk_add_f32 v[20:21], v[22:23], v[20:21] neg_lo:[0,1] neg_hi:[0,1]
	v_lshlrev_b32_e32 v0, 7, v116
	v_cvt_pk_bf16_f32 v18, v18, v19
	v_cvt_pk_bf16_f32 v19, v20, v21
	v_lshl_add_u64 v[16:17], v[16:17], 0, v[0:1]
	global_store_dwordx2 v[16:17], v[18:19], off
	ds_read_b128 v[16:19], v115 offset:40192
	s_waitcnt lgkmcnt(0)
	v_mfma_f32_16x16x32_bf16 v[2:5], v[2:5], v[16:19], 0
	v_mfma_f32_16x16x32_bf16 v[6:9], v[6:9], v[10:13], 0
	s_nop 7
	v_sub_f32_e32 v5, v5, v9
	v_sub_f32_e32 v4, v4, v8
	v_sub_f32_e32 v3, v3, v7
	v_sub_f32_e32 v2, v2, v6
	v_cvt_pk_bf16_f32 v2, v2, v3
	v_cvt_pk_bf16_f32 v3, v4, v5
	v_lshl_add_u64 v[4:5], v[14:15], 0, v[0:1]
	global_store_dwordx2 v[4:5], v[2:3], off
	s_barrier
	s_cbranch_scc1 .LBB0_371
